# CHAIN gate reads: last-use multiplier tile loaded non-temporal so the divisor tile (re-read one K-loop later) is favoured in L2
# speedup vs baseline: 1.0115x; 1.0046x over previous
.LBB0_355:
	v_readlane_b32 s0, v253, 25
	v_readlane_b32 s2, v253, 22
	s_lshl_b32 s1, s52, 2
	s_mul_i32 s0, s0, 12
	s_add_i32 s1, s2, s1
	s_add_i32 s0, s1, s0
	s_ashr_i32 s1, s0, 31
	s_lshl_b64 s[0:1], s[0:1], 17
	s_add_u32 s0, s50, s0
	s_addc_u32 s1, s51, s1
	s_add_u32 s2, s0, 0x80000
	s_addc_u32 s3, s1, 0
	v_lshlrev_b32_e32 v3, 3, v245
	v_lshl_add_u32 v2, v246, 7, v3
	v_lshlrev_b32_e32 v228, 1, v2
	s_cmp_eq_u32 s52, 2
	s_cbranch_scc1 .Lch_sub2
	global_load_dwordx4 v[132:135], v228, s[0:1] nt
	global_load_dwordx4 v[164:167], v228, s[2:3]
	s_add_u32 s0, s0, 0x2000
	s_addc_u32 s1, s1, 0
	s_add_u32 s2, s2, 0x2000
	s_addc_u32 s3, s3, 0
	global_load_dwordx4 v[136:139], v228, s[0:1] nt
	global_load_dwordx4 v[168:171], v228, s[2:3]
	s_add_u32 s0, s0, 0x2000
	s_addc_u32 s1, s1, 0
	s_add_u32 s2, s2, 0x2000
	s_addc_u32 s3, s3, 0
	global_load_dwordx4 v[140:143], v228, s[0:1] nt
	global_load_dwordx4 v[172:175], v228, s[2:3]
	s_add_u32 s0, s0, 0x2000
	s_addc_u32 s1, s1, 0
	s_add_u32 s2, s2, 0x2000
	s_addc_u32 s3, s3, 0
	global_load_dwordx4 v[144:147], v228, s[0:1] nt
	global_load_dwordx4 v[176:179], v228, s[2:3]
	s_add_u32 s0, s0, 0x2000
	s_addc_u32 s1, s1, 0
	s_add_u32 s2, s2, 0x2000
	s_addc_u32 s3, s3, 0
	global_load_dwordx4 v[148:151], v228, s[0:1] nt
	global_load_dwordx4 v[180:183], v228, s[2:3]
	s_add_u32 s0, s0, 0x2000
	s_addc_u32 s1, s1, 0
	s_add_u32 s2, s2, 0x2000
	s_addc_u32 s3, s3, 0
	global_load_dwordx4 v[152:155], v228, s[0:1] nt
	global_load_dwordx4 v[184:187], v228, s[2:3]
	s_add_u32 s0, s0, 0x2000
	s_addc_u32 s1, s1, 0
	s_add_u32 s2, s2, 0x2000
	s_addc_u32 s3, s3, 0
	global_load_dwordx4 v[156:159], v228, s[0:1] nt
	global_load_dwordx4 v[188:191], v228, s[2:3]
	s_add_u32 s0, s0, 0x2000
	s_addc_u32 s1, s1, 0
	s_add_u32 s2, s2, 0x2000
	s_addc_u32 s3, s3, 0
	global_load_dwordx4 v[160:163], v228, s[0:1] nt
	global_load_dwordx4 v[192:195], v228, s[2:3]
	s_add_u32 s0, s0, 0x2000
	s_addc_u32 s1, s1, 0
	s_add_u32 s2, s2, 0x2000
	s_addc_u32 s3, s3, 0
	s_waitcnt vmcnt(0)
	v_lshlrev_b32_e32 v208, 16, v132
	v_and_b32_e32 v209, 0xffff0000, v132
	v_lshlrev_b32_e32 v210, 16, v133
	v_and_b32_e32 v211, 0xffff0000, v133
	v_lshlrev_b32_e32 v212, 16, v134
	v_and_b32_e32 v213, 0xffff0000, v134
	v_lshlrev_b32_e32 v214, 16, v135
	v_and_b32_e32 v215, 0xffff0000, v135
	v_lshlrev_b32_e32 v236, 16, v164
	v_and_b32_e32 v237, 0xffff0000, v164
	v_lshlrev_b32_e32 v238, 16, v165
	v_and_b32_e32 v239, 0xffff0000, v165
	v_lshlrev_b32_e32 v230, 16, v166
	v_and_b32_e32 v231, 0xffff0000, v166
	v_lshlrev_b32_e32 v2, 16, v167
	v_and_b32_e32 v3, 0xffff0000, v167
	v_rcp_f32_e32 v236, v236
	v_rcp_f32_e32 v237, v237
	v_rcp_f32_e32 v238, v238
	v_rcp_f32_e32 v239, v239
	v_rcp_f32_e32 v230, v230
	v_rcp_f32_e32 v231, v231
	v_rcp_f32_e32 v2, v2
	v_rcp_f32_e32 v3, v3
	v_pk_mul_f32 v[236:237], v[236:237], v[208:209]
	v_pk_mul_f32 v[238:239], v[238:239], v[210:211]
	v_pk_mul_f32 v[230:231], v[230:231], v[212:213]
	v_pk_mul_f32 v[2:3], v[2:3], v[214:215]
	v_pk_mul_f32 v[128:129], v[128:129], v[236:237]
	v_pk_mul_f32 v[130:131], v[130:131], v[238:239]
	v_pk_mul_f32 v[124:125], v[124:125], v[230:231]
	v_pk_mul_f32 v[126:127], v[126:127], v[2:3]
	global_load_dwordx4 v[132:135], v228, s[0:1] nt
	global_load_dwordx4 v[164:167], v228, s[2:3]
	s_add_u32 s0, s0, 0x2000
	s_addc_u32 s1, s1, 0
	s_add_u32 s2, s2, 0x2000
	s_addc_u32 s3, s3, 0
	v_lshlrev_b32_e32 v208, 16, v136
	v_and_b32_e32 v209, 0xffff0000, v136
	v_lshlrev_b32_e32 v210, 16, v137
	v_and_b32_e32 v211, 0xffff0000, v137
	v_lshlrev_b32_e32 v212, 16, v138
	v_and_b32_e32 v213, 0xffff0000, v138
	v_lshlrev_b32_e32 v214, 16, v139
	v_and_b32_e32 v215, 0xffff0000, v139
	v_lshlrev_b32_e32 v236, 16, v168
	v_and_b32_e32 v237, 0xffff0000, v168
	v_lshlrev_b32_e32 v238, 16, v169
	v_and_b32_e32 v239, 0xffff0000, v169
	v_lshlrev_b32_e32 v230, 16, v170
	v_and_b32_e32 v231, 0xffff0000, v170
	v_lshlrev_b32_e32 v2, 16, v171
	v_and_b32_e32 v3, 0xffff0000, v171
	v_rcp_f32_e32 v236, v236
	v_rcp_f32_e32 v237, v237
	v_rcp_f32_e32 v238, v238
	v_rcp_f32_e32 v239, v239
	v_rcp_f32_e32 v230, v230
	v_rcp_f32_e32 v231, v231
	v_rcp_f32_e32 v2, v2
	v_rcp_f32_e32 v3, v3
	v_pk_mul_f32 v[236:237], v[236:237], v[208:209]
	v_pk_mul_f32 v[238:239], v[238:239], v[210:211]
	v_pk_mul_f32 v[230:231], v[230:231], v[212:213]
	v_pk_mul_f32 v[2:3], v[2:3], v[214:215]
	v_pk_mul_f32 v[96:97], v[96:97], v[236:237]
	v_pk_mul_f32 v[98:99], v[98:99], v[238:239]
	v_pk_mul_f32 v[92:93], v[92:93], v[230:231]
	v_pk_mul_f32 v[94:95], v[94:95], v[2:3]
	global_load_dwordx4 v[136:139], v228, s[0:1] nt
	global_load_dwordx4 v[168:171], v228, s[2:3]
	s_add_u32 s0, s0, 0x2000
	s_addc_u32 s1, s1, 0
	s_add_u32 s2, s2, 0x2000
	s_addc_u32 s3, s3, 0
	v_lshlrev_b32_e32 v208, 16, v140
	v_and_b32_e32 v209, 0xffff0000, v140
	v_lshlrev_b32_e32 v210, 16, v141
	v_and_b32_e32 v211, 0xffff0000, v141
	v_lshlrev_b32_e32 v212, 16, v142
	v_and_b32_e32 v213, 0xffff0000, v142
	v_lshlrev_b32_e32 v214, 16, v143
	v_and_b32_e32 v215, 0xffff0000, v143
	v_lshlrev_b32_e32 v236, 16, v172
	v_and_b32_e32 v237, 0xffff0000, v172
	v_lshlrev_b32_e32 v238, 16, v173
	v_and_b32_e32 v239, 0xffff0000, v173
	v_lshlrev_b32_e32 v230, 16, v174
	v_and_b32_e32 v231, 0xffff0000, v174
	v_lshlrev_b32_e32 v2, 16, v175
	v_and_b32_e32 v3, 0xffff0000, v175
	v_rcp_f32_e32 v236, v236
	v_rcp_f32_e32 v237, v237
	v_rcp_f32_e32 v238, v238
	v_rcp_f32_e32 v239, v239
	v_rcp_f32_e32 v230, v230
	v_rcp_f32_e32 v231, v231
	v_rcp_f32_e32 v2, v2
	v_rcp_f32_e32 v3, v3
	v_pk_mul_f32 v[236:237], v[236:237], v[208:209]
	v_pk_mul_f32 v[238:239], v[238:239], v[210:211]
	v_pk_mul_f32 v[230:231], v[230:231], v[212:213]
	v_pk_mul_f32 v[2:3], v[2:3], v[214:215]
	v_pk_mul_f32 v[120:121], v[120:121], v[236:237]
	v_pk_mul_f32 v[122:123], v[122:123], v[238:239]
	v_pk_mul_f32 v[116:117], v[116:117], v[230:231]
	v_pk_mul_f32 v[118:119], v[118:119], v[2:3]
	global_load_dwordx4 v[140:143], v228, s[0:1] nt
	global_load_dwordx4 v[172:175], v228, s[2:3]
	s_add_u32 s0, s0, 0x2000
	s_addc_u32 s1, s1, 0
	s_add_u32 s2, s2, 0x2000
	s_addc_u32 s3, s3, 0
	v_lshlrev_b32_e32 v208, 16, v144
	v_and_b32_e32 v209, 0xffff0000, v144
	v_lshlrev_b32_e32 v210, 16, v145
	v_and_b32_e32 v211, 0xffff0000, v145
	v_lshlrev_b32_e32 v212, 16, v146
	v_and_b32_e32 v213, 0xffff0000, v146
	v_lshlrev_b32_e32 v214, 16, v147
	v_and_b32_e32 v215, 0xffff0000, v147
	v_lshlrev_b32_e32 v236, 16, v176
	v_and_b32_e32 v237, 0xffff0000, v176
	v_lshlrev_b32_e32 v238, 16, v177
	v_and_b32_e32 v239, 0xffff0000, v177
	v_lshlrev_b32_e32 v230, 16, v178
	v_and_b32_e32 v231, 0xffff0000, v178
	v_lshlrev_b32_e32 v2, 16, v179
	v_and_b32_e32 v3, 0xffff0000, v179
	v_rcp_f32_e32 v236, v236
	v_rcp_f32_e32 v237, v237
	v_rcp_f32_e32 v238, v238
	v_rcp_f32_e32 v239, v239
	v_rcp_f32_e32 v230, v230
	v_rcp_f32_e32 v231, v231
	v_rcp_f32_e32 v2, v2
	v_rcp_f32_e32 v3, v3
	v_pk_mul_f32 v[236:237], v[236:237], v[208:209]
	v_pk_mul_f32 v[238:239], v[238:239], v[210:211]
	v_pk_mul_f32 v[230:231], v[230:231], v[212:213]
	v_pk_mul_f32 v[2:3], v[2:3], v[214:215]
	v_pk_mul_f32 v[88:89], v[88:89], v[236:237]
	v_pk_mul_f32 v[90:91], v[90:91], v[238:239]
	v_pk_mul_f32 v[84:85], v[84:85], v[230:231]
	v_pk_mul_f32 v[86:87], v[86:87], v[2:3]
	global_load_dwordx4 v[144:147], v228, s[0:1] nt
	global_load_dwordx4 v[176:179], v228, s[2:3]
	s_add_u32 s0, s0, 0x2000
	s_addc_u32 s1, s1, 0
	s_add_u32 s2, s2, 0x2000
	s_addc_u32 s3, s3, 0
	v_lshlrev_b32_e32 v208, 16, v148
	v_and_b32_e32 v209, 0xffff0000, v148
	v_lshlrev_b32_e32 v210, 16, v149
	v_and_b32_e32 v211, 0xffff0000, v149
	v_lshlrev_b32_e32 v212, 16, v150
	v_and_b32_e32 v213, 0xffff0000, v150
	v_lshlrev_b32_e32 v214, 16, v151
	v_and_b32_e32 v215, 0xffff0000, v151
	v_lshlrev_b32_e32 v236, 16, v180
	v_and_b32_e32 v237, 0xffff0000, v180
	v_lshlrev_b32_e32 v238, 16, v181
	v_and_b32_e32 v239, 0xffff0000, v181
	v_lshlrev_b32_e32 v230, 16, v182
	v_and_b32_e32 v231, 0xffff0000, v182
	v_lshlrev_b32_e32 v2, 16, v183
	v_and_b32_e32 v3, 0xffff0000, v183
	v_rcp_f32_e32 v236, v236
	v_rcp_f32_e32 v237, v237
	v_rcp_f32_e32 v238, v238
	v_rcp_f32_e32 v239, v239
	v_rcp_f32_e32 v230, v230
	v_rcp_f32_e32 v231, v231
	v_rcp_f32_e32 v2, v2
	v_rcp_f32_e32 v3, v3
	v_pk_mul_f32 v[236:237], v[236:237], v[208:209]
	v_pk_mul_f32 v[238:239], v[238:239], v[210:211]
	v_pk_mul_f32 v[230:231], v[230:231], v[212:213]
	v_pk_mul_f32 v[2:3], v[2:3], v[214:215]
	v_pk_mul_f32 v[112:113], v[112:113], v[236:237]
	v_pk_mul_f32 v[114:115], v[114:115], v[238:239]
	v_pk_mul_f32 v[108:109], v[108:109], v[230:231]
	v_pk_mul_f32 v[110:111], v[110:111], v[2:3]
	global_load_dwordx4 v[148:151], v228, s[0:1] nt
	global_load_dwordx4 v[180:183], v228, s[2:3]
	s_add_u32 s0, s0, 0x2000
	s_addc_u32 s1, s1, 0
	s_add_u32 s2, s2, 0x2000
	s_addc_u32 s3, s3, 0
	v_lshlrev_b32_e32 v208, 16, v152
	v_and_b32_e32 v209, 0xffff0000, v152
	v_lshlrev_b32_e32 v210, 16, v153
	v_and_b32_e32 v211, 0xffff0000, v153
	v_lshlrev_b32_e32 v212, 16, v154
	v_and_b32_e32 v213, 0xffff0000, v154
	v_lshlrev_b32_e32 v214, 16, v155
	v_and_b32_e32 v215, 0xffff0000, v155
	v_lshlrev_b32_e32 v236, 16, v184
	v_and_b32_e32 v237, 0xffff0000, v184
	v_lshlrev_b32_e32 v238, 16, v185
	v_and_b32_e32 v239, 0xffff0000, v185
	v_lshlrev_b32_e32 v230, 16, v186
	v_and_b32_e32 v231, 0xffff0000, v186
	v_lshlrev_b32_e32 v2, 16, v187
	v_and_b32_e32 v3, 0xffff0000, v187
	v_rcp_f32_e32 v236, v236
	v_rcp_f32_e32 v237, v237
	v_rcp_f32_e32 v238, v238
	v_rcp_f32_e32 v239, v239
	v_rcp_f32_e32 v230, v230
	v_rcp_f32_e32 v231, v231
	v_rcp_f32_e32 v2, v2
	v_rcp_f32_e32 v3, v3
	v_pk_mul_f32 v[236:237], v[236:237], v[208:209]
	v_pk_mul_f32 v[238:239], v[238:239], v[210:211]
	v_pk_mul_f32 v[230:231], v[230:231], v[212:213]
	v_pk_mul_f32 v[2:3], v[2:3], v[214:215]
	v_pk_mul_f32 v[80:81], v[80:81], v[236:237]
	v_pk_mul_f32 v[82:83], v[82:83], v[238:239]
	v_pk_mul_f32 v[76:77], v[76:77], v[230:231]
	v_pk_mul_f32 v[78:79], v[78:79], v[2:3]
	global_load_dwordx4 v[152:155], v228, s[0:1] nt
	global_load_dwordx4 v[184:187], v228, s[2:3]
	s_add_u32 s0, s0, 0x2000
	s_addc_u32 s1, s1, 0
	s_add_u32 s2, s2, 0x2000
	s_addc_u32 s3, s3, 0
	v_lshlrev_b32_e32 v208, 16, v156
	v_and_b32_e32 v209, 0xffff0000, v156
	v_lshlrev_b32_e32 v210, 16, v157
	v_and_b32_e32 v211, 0xffff0000, v157
	v_lshlrev_b32_e32 v212, 16, v158
	v_and_b32_e32 v213, 0xffff0000, v158
	v_lshlrev_b32_e32 v214, 16, v159
	v_and_b32_e32 v215, 0xffff0000, v159
	v_lshlrev_b32_e32 v236, 16, v188
	v_and_b32_e32 v237, 0xffff0000, v188
	v_lshlrev_b32_e32 v238, 16, v189
	v_and_b32_e32 v239, 0xffff0000, v189
	v_lshlrev_b32_e32 v230, 16, v190
	v_and_b32_e32 v231, 0xffff0000, v190
	v_lshlrev_b32_e32 v2, 16, v191
	v_and_b32_e32 v3, 0xffff0000, v191
	v_rcp_f32_e32 v236, v236
	v_rcp_f32_e32 v237, v237
	v_rcp_f32_e32 v238, v238
	v_rcp_f32_e32 v239, v239
	v_rcp_f32_e32 v230, v230
	v_rcp_f32_e32 v231, v231
	v_rcp_f32_e32 v2, v2
	v_rcp_f32_e32 v3, v3
	v_pk_mul_f32 v[236:237], v[236:237], v[208:209]
	v_pk_mul_f32 v[238:239], v[238:239], v[210:211]
	v_pk_mul_f32 v[230:231], v[230:231], v[212:213]
	v_pk_mul_f32 v[2:3], v[2:3], v[214:215]
	v_pk_mul_f32 v[104:105], v[104:105], v[236:237]
	v_pk_mul_f32 v[106:107], v[106:107], v[238:239]
	v_pk_mul_f32 v[100:101], v[100:101], v[230:231]
	v_pk_mul_f32 v[102:103], v[102:103], v[2:3]
	global_load_dwordx4 v[156:159], v228, s[0:1] nt
	global_load_dwordx4 v[188:191], v228, s[2:3]
	s_add_u32 s0, s0, 0x2000
	s_addc_u32 s1, s1, 0
	s_add_u32 s2, s2, 0x2000
	s_addc_u32 s3, s3, 0
	v_lshlrev_b32_e32 v208, 16, v160
	v_and_b32_e32 v209, 0xffff0000, v160
	v_lshlrev_b32_e32 v210, 16, v161
	v_and_b32_e32 v211, 0xffff0000, v161
	v_lshlrev_b32_e32 v212, 16, v162
	v_and_b32_e32 v213, 0xffff0000, v162
	v_lshlrev_b32_e32 v214, 16, v163
	v_and_b32_e32 v215, 0xffff0000, v163
	v_lshlrev_b32_e32 v236, 16, v192
	v_and_b32_e32 v237, 0xffff0000, v192
	v_lshlrev_b32_e32 v238, 16, v193
	v_and_b32_e32 v239, 0xffff0000, v193
	v_lshlrev_b32_e32 v230, 16, v194
	v_and_b32_e32 v231, 0xffff0000, v194
	v_lshlrev_b32_e32 v2, 16, v195
	v_and_b32_e32 v3, 0xffff0000, v195
	v_rcp_f32_e32 v236, v236
	v_rcp_f32_e32 v237, v237
	v_rcp_f32_e32 v238, v238
	v_rcp_f32_e32 v239, v239
	v_rcp_f32_e32 v230, v230
	v_rcp_f32_e32 v231, v231
	v_rcp_f32_e32 v2, v2
	v_rcp_f32_e32 v3, v3
	v_pk_mul_f32 v[236:237], v[236:237], v[208:209]
	v_pk_mul_f32 v[238:239], v[238:239], v[210:211]
	v_pk_mul_f32 v[230:231], v[230:231], v[212:213]
	v_pk_mul_f32 v[2:3], v[2:3], v[214:215]
	v_pk_mul_f32 v[72:73], v[72:73], v[236:237]
	v_pk_mul_f32 v[74:75], v[74:75], v[238:239]
	v_pk_mul_f32 v[68:69], v[68:69], v[230:231]
	v_pk_mul_f32 v[70:71], v[70:71], v[2:3]
	global_load_dwordx4 v[160:163], v228, s[0:1] nt
	global_load_dwordx4 v[192:195], v228, s[2:3]
	s_add_u32 s0, s0, 0x2000
	s_addc_u32 s1, s1, 0
	s_add_u32 s2, s2, 0x2000
	s_addc_u32 s3, s3, 0
	s_waitcnt vmcnt(14)
	v_lshlrev_b32_e32 v208, 16, v132
	v_and_b32_e32 v209, 0xffff0000, v132
	v_lshlrev_b32_e32 v210, 16, v133
	v_and_b32_e32 v211, 0xffff0000, v133
	v_lshlrev_b32_e32 v212, 16, v134
	v_and_b32_e32 v213, 0xffff0000, v134
	v_lshlrev_b32_e32 v214, 16, v135
	v_and_b32_e32 v215, 0xffff0000, v135
	v_lshlrev_b32_e32 v236, 16, v164
	v_and_b32_e32 v237, 0xffff0000, v164
	v_lshlrev_b32_e32 v238, 16, v165
	v_and_b32_e32 v239, 0xffff0000, v165
	v_lshlrev_b32_e32 v230, 16, v166
	v_and_b32_e32 v231, 0xffff0000, v166
	v_lshlrev_b32_e32 v2, 16, v167
	v_and_b32_e32 v3, 0xffff0000, v167
	v_rcp_f32_e32 v236, v236
	v_rcp_f32_e32 v237, v237
	v_rcp_f32_e32 v238, v238
	v_rcp_f32_e32 v239, v239
	v_rcp_f32_e32 v230, v230
	v_rcp_f32_e32 v231, v231
	v_rcp_f32_e32 v2, v2
	v_rcp_f32_e32 v3, v3
	v_pk_mul_f32 v[236:237], v[236:237], v[208:209]
	v_pk_mul_f32 v[238:239], v[238:239], v[210:211]
	v_pk_mul_f32 v[230:231], v[230:231], v[212:213]
	v_pk_mul_f32 v[2:3], v[2:3], v[214:215]
	v_pk_mul_f32 v[64:65], v[64:65], v[236:237]
	v_pk_mul_f32 v[66:67], v[66:67], v[238:239]
	v_pk_mul_f32 v[60:61], v[60:61], v[230:231]
	v_pk_mul_f32 v[62:63], v[62:63], v[2:3]
	s_waitcnt vmcnt(12)
	v_lshlrev_b32_e32 v208, 16, v136
	v_and_b32_e32 v209, 0xffff0000, v136
	v_lshlrev_b32_e32 v210, 16, v137
	v_and_b32_e32 v211, 0xffff0000, v137
	v_lshlrev_b32_e32 v212, 16, v138
	v_and_b32_e32 v213, 0xffff0000, v138
	v_lshlrev_b32_e32 v214, 16, v139
	v_and_b32_e32 v215, 0xffff0000, v139
	v_lshlrev_b32_e32 v236, 16, v168
	v_and_b32_e32 v237, 0xffff0000, v168
	v_lshlrev_b32_e32 v238, 16, v169
	v_and_b32_e32 v239, 0xffff0000, v169
	v_lshlrev_b32_e32 v230, 16, v170
	v_and_b32_e32 v231, 0xffff0000, v170
	v_lshlrev_b32_e32 v2, 16, v171
	v_and_b32_e32 v3, 0xffff0000, v171
	v_rcp_f32_e32 v236, v236
	v_rcp_f32_e32 v237, v237
	v_rcp_f32_e32 v238, v238
	v_rcp_f32_e32 v239, v239
	v_rcp_f32_e32 v230, v230
	v_rcp_f32_e32 v231, v231
	v_rcp_f32_e32 v2, v2
	v_rcp_f32_e32 v3, v3
	v_pk_mul_f32 v[236:237], v[236:237], v[208:209]
	v_pk_mul_f32 v[238:239], v[238:239], v[210:211]
	v_pk_mul_f32 v[230:231], v[230:231], v[212:213]
	v_pk_mul_f32 v[2:3], v[2:3], v[214:215]
	v_pk_mul_f32 v[32:33], v[32:33], v[236:237]
	v_pk_mul_f32 v[34:35], v[34:35], v[238:239]
	v_pk_mul_f32 v[28:29], v[28:29], v[230:231]
	v_pk_mul_f32 v[30:31], v[30:31], v[2:3]
	s_waitcnt vmcnt(10)
	v_lshlrev_b32_e32 v208, 16, v140
	v_and_b32_e32 v209, 0xffff0000, v140
	v_lshlrev_b32_e32 v210, 16, v141
	v_and_b32_e32 v211, 0xffff0000, v141
	v_lshlrev_b32_e32 v212, 16, v142
	v_and_b32_e32 v213, 0xffff0000, v142
	v_lshlrev_b32_e32 v214, 16, v143
	v_and_b32_e32 v215, 0xffff0000, v143
	v_lshlrev_b32_e32 v236, 16, v172
	v_and_b32_e32 v237, 0xffff0000, v172
	v_lshlrev_b32_e32 v238, 16, v173
	v_and_b32_e32 v239, 0xffff0000, v173
	v_lshlrev_b32_e32 v230, 16, v174
	v_and_b32_e32 v231, 0xffff0000, v174
	v_lshlrev_b32_e32 v2, 16, v175
	v_and_b32_e32 v3, 0xffff0000, v175
	v_rcp_f32_e32 v236, v236
	v_rcp_f32_e32 v237, v237
	v_rcp_f32_e32 v238, v238
	v_rcp_f32_e32 v239, v239
	v_rcp_f32_e32 v230, v230
	v_rcp_f32_e32 v231, v231
	v_rcp_f32_e32 v2, v2
	v_rcp_f32_e32 v3, v3
	v_pk_mul_f32 v[236:237], v[236:237], v[208:209]
	v_pk_mul_f32 v[238:239], v[238:239], v[210:211]
	v_pk_mul_f32 v[230:231], v[230:231], v[212:213]
	v_pk_mul_f32 v[2:3], v[2:3], v[214:215]
	v_pk_mul_f32 v[56:57], v[56:57], v[236:237]
	v_pk_mul_f32 v[58:59], v[58:59], v[238:239]
	v_pk_mul_f32 v[52:53], v[52:53], v[230:231]
	v_pk_mul_f32 v[54:55], v[54:55], v[2:3]
	s_waitcnt vmcnt(8)
	v_lshlrev_b32_e32 v208, 16, v144
	v_and_b32_e32 v209, 0xffff0000, v144
	v_lshlrev_b32_e32 v210, 16, v145
	v_and_b32_e32 v211, 0xffff0000, v145
	v_lshlrev_b32_e32 v212, 16, v146
	v_and_b32_e32 v213, 0xffff0000, v146
	v_lshlrev_b32_e32 v214, 16, v147
	v_and_b32_e32 v215, 0xffff0000, v147
	v_lshlrev_b32_e32 v236, 16, v176
	v_and_b32_e32 v237, 0xffff0000, v176
	v_lshlrev_b32_e32 v238, 16, v177
	v_and_b32_e32 v239, 0xffff0000, v177
	v_lshlrev_b32_e32 v230, 16, v178
	v_and_b32_e32 v231, 0xffff0000, v178
	v_lshlrev_b32_e32 v2, 16, v179
	v_and_b32_e32 v3, 0xffff0000, v179
	v_rcp_f32_e32 v236, v236
	v_rcp_f32_e32 v237, v237
	v_rcp_f32_e32 v238, v238
	v_rcp_f32_e32 v239, v239
	v_rcp_f32_e32 v230, v230
	v_rcp_f32_e32 v231, v231
	v_rcp_f32_e32 v2, v2
	v_rcp_f32_e32 v3, v3
	v_pk_mul_f32 v[236:237], v[236:237], v[208:209]
	v_pk_mul_f32 v[238:239], v[238:239], v[210:211]
	v_pk_mul_f32 v[230:231], v[230:231], v[212:213]
	v_pk_mul_f32 v[2:3], v[2:3], v[214:215]
	v_pk_mul_f32 v[24:25], v[24:25], v[236:237]
	v_pk_mul_f32 v[26:27], v[26:27], v[238:239]
	v_pk_mul_f32 v[20:21], v[20:21], v[230:231]
	v_pk_mul_f32 v[22:23], v[22:23], v[2:3]
	s_waitcnt vmcnt(6)
	v_lshlrev_b32_e32 v208, 16, v148
	v_and_b32_e32 v209, 0xffff0000, v148
	v_lshlrev_b32_e32 v210, 16, v149
	v_and_b32_e32 v211, 0xffff0000, v149
	v_lshlrev_b32_e32 v212, 16, v150
	v_and_b32_e32 v213, 0xffff0000, v150
	v_lshlrev_b32_e32 v214, 16, v151
	v_and_b32_e32 v215, 0xffff0000, v151
	v_lshlrev_b32_e32 v236, 16, v180
	v_and_b32_e32 v237, 0xffff0000, v180
	v_lshlrev_b32_e32 v238, 16, v181
	v_and_b32_e32 v239, 0xffff0000, v181
	v_lshlrev_b32_e32 v230, 16, v182
	v_and_b32_e32 v231, 0xffff0000, v182
	v_lshlrev_b32_e32 v2, 16, v183
	v_and_b32_e32 v3, 0xffff0000, v183
	v_rcp_f32_e32 v236, v236
	v_rcp_f32_e32 v237, v237
	v_rcp_f32_e32 v238, v238
	v_rcp_f32_e32 v239, v239
	v_rcp_f32_e32 v230, v230
	v_rcp_f32_e32 v231, v231
	v_rcp_f32_e32 v2, v2
	v_rcp_f32_e32 v3, v3
	v_pk_mul_f32 v[236:237], v[236:237], v[208:209]
	v_pk_mul_f32 v[238:239], v[238:239], v[210:211]
	v_pk_mul_f32 v[230:231], v[230:231], v[212:213]
	v_pk_mul_f32 v[2:3], v[2:3], v[214:215]
	v_pk_mul_f32 v[48:49], v[48:49], v[236:237]
	v_pk_mul_f32 v[50:51], v[50:51], v[238:239]
	v_pk_mul_f32 v[44:45], v[44:45], v[230:231]
	v_pk_mul_f32 v[46:47], v[46:47], v[2:3]
	s_waitcnt vmcnt(4)
	v_lshlrev_b32_e32 v208, 16, v152
	v_and_b32_e32 v209, 0xffff0000, v152
	v_lshlrev_b32_e32 v210, 16, v153
	v_and_b32_e32 v211, 0xffff0000, v153
	v_lshlrev_b32_e32 v212, 16, v154
	v_and_b32_e32 v213, 0xffff0000, v154
	v_lshlrev_b32_e32 v214, 16, v155
	v_and_b32_e32 v215, 0xffff0000, v155
	v_lshlrev_b32_e32 v236, 16, v184
	v_and_b32_e32 v237, 0xffff0000, v184
	v_lshlrev_b32_e32 v238, 16, v185
	v_and_b32_e32 v239, 0xffff0000, v185
	v_lshlrev_b32_e32 v230, 16, v186
	v_and_b32_e32 v231, 0xffff0000, v186
	v_lshlrev_b32_e32 v2, 16, v187
	v_and_b32_e32 v3, 0xffff0000, v187
	v_rcp_f32_e32 v236, v236
	v_rcp_f32_e32 v237, v237
	v_rcp_f32_e32 v238, v238
	v_rcp_f32_e32 v239, v239
	v_rcp_f32_e32 v230, v230
	v_rcp_f32_e32 v231, v231
	v_rcp_f32_e32 v2, v2
	v_rcp_f32_e32 v3, v3
	v_pk_mul_f32 v[236:237], v[236:237], v[208:209]
	v_pk_mul_f32 v[238:239], v[238:239], v[210:211]
	v_pk_mul_f32 v[230:231], v[230:231], v[212:213]
	v_pk_mul_f32 v[2:3], v[2:3], v[214:215]
	v_pk_mul_f32 v[16:17], v[16:17], v[236:237]
	v_pk_mul_f32 v[18:19], v[18:19], v[238:239]
	v_pk_mul_f32 v[12:13], v[12:13], v[230:231]
	v_pk_mul_f32 v[14:15], v[14:15], v[2:3]
	s_waitcnt vmcnt(2)
	v_lshlrev_b32_e32 v208, 16, v156
	v_and_b32_e32 v209, 0xffff0000, v156
	v_lshlrev_b32_e32 v210, 16, v157
	v_and_b32_e32 v211, 0xffff0000, v157
	v_lshlrev_b32_e32 v212, 16, v158
	v_and_b32_e32 v213, 0xffff0000, v158
	v_lshlrev_b32_e32 v214, 16, v159
	v_and_b32_e32 v215, 0xffff0000, v159
	v_lshlrev_b32_e32 v236, 16, v188
	v_and_b32_e32 v237, 0xffff0000, v188
	v_lshlrev_b32_e32 v238, 16, v189
	v_and_b32_e32 v239, 0xffff0000, v189
	v_lshlrev_b32_e32 v230, 16, v190
	v_and_b32_e32 v231, 0xffff0000, v190
	v_lshlrev_b32_e32 v2, 16, v191
	v_and_b32_e32 v3, 0xffff0000, v191
	v_rcp_f32_e32 v236, v236
	v_rcp_f32_e32 v237, v237
	v_rcp_f32_e32 v238, v238
	v_rcp_f32_e32 v239, v239
	v_rcp_f32_e32 v230, v230
	v_rcp_f32_e32 v231, v231
	v_rcp_f32_e32 v2, v2
	v_rcp_f32_e32 v3, v3
	v_pk_mul_f32 v[236:237], v[236:237], v[208:209]
	v_pk_mul_f32 v[238:239], v[238:239], v[210:211]
	v_pk_mul_f32 v[230:231], v[230:231], v[212:213]
	v_pk_mul_f32 v[2:3], v[2:3], v[214:215]
	v_pk_mul_f32 v[40:41], v[40:41], v[236:237]
	v_pk_mul_f32 v[42:43], v[42:43], v[238:239]
	v_pk_mul_f32 v[36:37], v[36:37], v[230:231]
	v_pk_mul_f32 v[38:39], v[38:39], v[2:3]
	s_waitcnt vmcnt(0)
	v_lshlrev_b32_e32 v208, 16, v160
	v_and_b32_e32 v209, 0xffff0000, v160
	v_lshlrev_b32_e32 v210, 16, v161
	v_and_b32_e32 v211, 0xffff0000, v161
	v_lshlrev_b32_e32 v212, 16, v162
	v_and_b32_e32 v213, 0xffff0000, v162
	v_lshlrev_b32_e32 v214, 16, v163
	v_and_b32_e32 v215, 0xffff0000, v163
	v_lshlrev_b32_e32 v236, 16, v192
	v_and_b32_e32 v237, 0xffff0000, v192
	v_lshlrev_b32_e32 v238, 16, v193
	v_and_b32_e32 v239, 0xffff0000, v193
	v_lshlrev_b32_e32 v230, 16, v194
	v_and_b32_e32 v231, 0xffff0000, v194
	v_lshlrev_b32_e32 v2, 16, v195
	v_and_b32_e32 v3, 0xffff0000, v195
	v_rcp_f32_e32 v236, v236
	v_rcp_f32_e32 v237, v237
	v_rcp_f32_e32 v238, v238
	v_rcp_f32_e32 v239, v239
	v_rcp_f32_e32 v230, v230
	v_rcp_f32_e32 v231, v231
	v_rcp_f32_e32 v2, v2
	v_rcp_f32_e32 v3, v3
	v_pk_mul_f32 v[236:237], v[236:237], v[208:209]
	v_pk_mul_f32 v[238:239], v[238:239], v[210:211]
	v_pk_mul_f32 v[230:231], v[230:231], v[212:213]
	v_pk_mul_f32 v[2:3], v[2:3], v[214:215]
	v_pk_mul_f32 v[8:9], v[8:9], v[236:237]
	v_pk_mul_f32 v[10:11], v[10:11], v[238:239]
	v_pk_mul_f32 v[4:5], v[4:5], v[230:231]
	v_pk_mul_f32 v[6:7], v[6:7], v[2:3]
	s_branch .Lch_done
.Lch_sub2:
	v_readlane_b32 s4, v253, 25
	s_nop 0
	s_lshl_b32 s4, s4, 8
	s_add_i32 s4, s4, s19
	s_ashr_i32 s5, s4, 31
	s_lshl_b64 s[4:5], s[4:5], 11
	s_add_u32 s4, s28, s4
	s_addc_u32 s5, s29, s5
	v_readlane_b32 s2, v253, 22
	s_nop 0
	s_lshl_b32 s2, s2, 9
	s_add_u32 s4, s4, s2
	s_addc_u32 s5, s5, 0
	s_lshl_b32 s2, s40, 1
	s_add_u32 s4, s4, s2
	s_addc_u32 s5, s5, 0
	v_lshlrev_b32_e32 v240, 11, v245
	v_lshl_add_u32 v240, v246, 4, v240
	global_load_dwordx4 v[132:135], v228, s[0:1] nt
	s_add_u32 s0, s0, 0x2000
	s_addc_u32 s1, s1, 0
	global_load_dwordx4 v[136:139], v228, s[0:1] nt
	s_add_u32 s0, s0, 0x2000
	s_addc_u32 s1, s1, 0
	global_load_dwordx4 v[140:143], v228, s[0:1] nt
	s_add_u32 s0, s0, 0x2000
	s_addc_u32 s1, s1, 0
	global_load_dwordx4 v[144:147], v228, s[0:1] nt
	s_add_u32 s0, s0, 0x2000
	s_addc_u32 s1, s1, 0
	global_load_dwordx4 v[148:151], v228, s[0:1] nt
	s_add_u32 s0, s0, 0x2000
	s_addc_u32 s1, s1, 0
	global_load_dwordx4 v[152:155], v228, s[0:1] nt
	s_add_u32 s0, s0, 0x2000
	s_addc_u32 s1, s1, 0
	global_load_dwordx4 v[156:159], v228, s[0:1] nt
	s_add_u32 s0, s0, 0x2000
	s_addc_u32 s1, s1, 0
	global_load_dwordx4 v[160:163], v228, s[0:1] nt
	s_add_u32 s0, s0, 0x2000
	s_addc_u32 s1, s1, 0
	s_waitcnt vmcnt(0)
	v_lshlrev_b32_e32 v208, 16, v132
	v_and_b32_e32 v209, 0xffff0000, v132
	v_lshlrev_b32_e32 v210, 16, v133
	v_and_b32_e32 v211, 0xffff0000, v133
	v_lshlrev_b32_e32 v212, 16, v134
	v_and_b32_e32 v213, 0xffff0000, v134
	v_lshlrev_b32_e32 v214, 16, v135
	v_and_b32_e32 v215, 0xffff0000, v135
	v_pk_mul_f32 v[236:237], v[128:129], v[208:209]
	v_pk_mul_f32 v[238:239], v[130:131], v[210:211]
	v_pk_mul_f32 v[230:231], v[124:125], v[212:213]
	v_pk_mul_f32 v[2:3], v[126:127], v[214:215]
	v_cvt_pk_bf16_f32 v208, v236, v237
	v_cvt_pk_bf16_f32 v209, v238, v239
	v_cvt_pk_bf16_f32 v210, v230, v231
	v_cvt_pk_bf16_f32 v211, v2, v3
	global_store_dwordx4 v240, v[208:211], s[4:5]
	global_load_dwordx4 v[132:135], v228, s[0:1] nt
	s_add_u32 s0, s0, 0x2000
	s_addc_u32 s1, s1, 0
	v_lshlrev_b32_e32 v208, 16, v136
	v_and_b32_e32 v209, 0xffff0000, v136
	v_lshlrev_b32_e32 v210, 16, v137
	v_and_b32_e32 v211, 0xffff0000, v137
	v_lshlrev_b32_e32 v212, 16, v138
	v_and_b32_e32 v213, 0xffff0000, v138
	v_lshlrev_b32_e32 v214, 16, v139
	v_and_b32_e32 v215, 0xffff0000, v139
	v_pk_mul_f32 v[236:237], v[96:97], v[208:209]
	v_pk_mul_f32 v[238:239], v[98:99], v[210:211]
	v_pk_mul_f32 v[230:231], v[92:93], v[212:213]
	v_pk_mul_f32 v[2:3], v[94:95], v[214:215]
	v_cvt_pk_bf16_f32 v208, v236, v237
	v_cvt_pk_bf16_f32 v209, v238, v239
	v_cvt_pk_bf16_f32 v210, v230, v231
	v_cvt_pk_bf16_f32 v211, v2, v3
	global_store_dwordx4 v240, v[208:211], s[4:5] offset:256
	s_add_u32 s4, s4, 0x8000
	s_addc_u32 s5, s5, 0
	global_load_dwordx4 v[136:139], v228, s[0:1] nt
	s_add_u32 s0, s0, 0x2000
	s_addc_u32 s1, s1, 0
	v_lshlrev_b32_e32 v208, 16, v140
	v_and_b32_e32 v209, 0xffff0000, v140
	v_lshlrev_b32_e32 v210, 16, v141
	v_and_b32_e32 v211, 0xffff0000, v141
	v_lshlrev_b32_e32 v212, 16, v142
	v_and_b32_e32 v213, 0xffff0000, v142
	v_lshlrev_b32_e32 v214, 16, v143
	v_and_b32_e32 v215, 0xffff0000, v143
	v_pk_mul_f32 v[236:237], v[120:121], v[208:209]
	v_pk_mul_f32 v[238:239], v[122:123], v[210:211]
	v_pk_mul_f32 v[230:231], v[116:117], v[212:213]
	v_pk_mul_f32 v[2:3], v[118:119], v[214:215]
	v_cvt_pk_bf16_f32 v208, v236, v237
	v_cvt_pk_bf16_f32 v209, v238, v239
	v_cvt_pk_bf16_f32 v210, v230, v231
	v_cvt_pk_bf16_f32 v211, v2, v3
	global_store_dwordx4 v240, v[208:211], s[4:5]
	global_load_dwordx4 v[140:143], v228, s[0:1] nt
	s_add_u32 s0, s0, 0x2000
	s_addc_u32 s1, s1, 0
	v_lshlrev_b32_e32 v208, 16, v144
	v_and_b32_e32 v209, 0xffff0000, v144
	v_lshlrev_b32_e32 v210, 16, v145
	v_and_b32_e32 v211, 0xffff0000, v145
	v_lshlrev_b32_e32 v212, 16, v146
	v_and_b32_e32 v213, 0xffff0000, v146
	v_lshlrev_b32_e32 v214, 16, v147
	v_and_b32_e32 v215, 0xffff0000, v147
	v_pk_mul_f32 v[236:237], v[88:89], v[208:209]
	v_pk_mul_f32 v[238:239], v[90:91], v[210:211]
	v_pk_mul_f32 v[230:231], v[84:85], v[212:213]
	v_pk_mul_f32 v[2:3], v[86:87], v[214:215]
	v_cvt_pk_bf16_f32 v208, v236, v237
	v_cvt_pk_bf16_f32 v209, v238, v239
	v_cvt_pk_bf16_f32 v210, v230, v231
	v_cvt_pk_bf16_f32 v211, v2, v3
	global_store_dwordx4 v240, v[208:211], s[4:5] offset:256
	s_add_u32 s4, s4, 0x8000
	s_addc_u32 s5, s5, 0
	global_load_dwordx4 v[144:147], v228, s[0:1] nt
	s_add_u32 s0, s0, 0x2000
	s_addc_u32 s1, s1, 0
	v_lshlrev_b32_e32 v208, 16, v148
	v_and_b32_e32 v209, 0xffff0000, v148
	v_lshlrev_b32_e32 v210, 16, v149
	v_and_b32_e32 v211, 0xffff0000, v149
	v_lshlrev_b32_e32 v212, 16, v150
	v_and_b32_e32 v213, 0xffff0000, v150
	v_lshlrev_b32_e32 v214, 16, v151
	v_and_b32_e32 v215, 0xffff0000, v151
	v_pk_mul_f32 v[236:237], v[112:113], v[208:209]
	v_pk_mul_f32 v[238:239], v[114:115], v[210:211]
	v_pk_mul_f32 v[230:231], v[108:109], v[212:213]
	v_pk_mul_f32 v[2:3], v[110:111], v[214:215]
	v_cvt_pk_bf16_f32 v208, v236, v237
	v_cvt_pk_bf16_f32 v209, v238, v239
	v_cvt_pk_bf16_f32 v210, v230, v231
	v_cvt_pk_bf16_f32 v211, v2, v3
	global_store_dwordx4 v240, v[208:211], s[4:5]
	global_load_dwordx4 v[148:151], v228, s[0:1] nt
	s_add_u32 s0, s0, 0x2000
	s_addc_u32 s1, s1, 0
	v_lshlrev_b32_e32 v208, 16, v152
	v_and_b32_e32 v209, 0xffff0000, v152
	v_lshlrev_b32_e32 v210, 16, v153
	v_and_b32_e32 v211, 0xffff0000, v153
	v_lshlrev_b32_e32 v212, 16, v154
	v_and_b32_e32 v213, 0xffff0000, v154
	v_lshlrev_b32_e32 v214, 16, v155
	v_and_b32_e32 v215, 0xffff0000, v155
	v_pk_mul_f32 v[236:237], v[80:81], v[208:209]
	v_pk_mul_f32 v[238:239], v[82:83], v[210:211]
	v_pk_mul_f32 v[230:231], v[76:77], v[212:213]
	v_pk_mul_f32 v[2:3], v[78:79], v[214:215]
	v_cvt_pk_bf16_f32 v208, v236, v237
	v_cvt_pk_bf16_f32 v209, v238, v239
	v_cvt_pk_bf16_f32 v210, v230, v231
	v_cvt_pk_bf16_f32 v211, v2, v3
	global_store_dwordx4 v240, v[208:211], s[4:5] offset:256
	s_add_u32 s4, s4, 0x8000
	s_addc_u32 s5, s5, 0
	global_load_dwordx4 v[152:155], v228, s[0:1] nt
	s_add_u32 s0, s0, 0x2000
	s_addc_u32 s1, s1, 0
	v_lshlrev_b32_e32 v208, 16, v156
	v_and_b32_e32 v209, 0xffff0000, v156
	v_lshlrev_b32_e32 v210, 16, v157
	v_and_b32_e32 v211, 0xffff0000, v157
	v_lshlrev_b32_e32 v212, 16, v158
	v_and_b32_e32 v213, 0xffff0000, v158
	v_lshlrev_b32_e32 v214, 16, v159
	v_and_b32_e32 v215, 0xffff0000, v159
	v_pk_mul_f32 v[236:237], v[104:105], v[208:209]
	v_pk_mul_f32 v[238:239], v[106:107], v[210:211]
	v_pk_mul_f32 v[230:231], v[100:101], v[212:213]
	v_pk_mul_f32 v[2:3], v[102:103], v[214:215]
	v_cvt_pk_bf16_f32 v208, v236, v237
	v_cvt_pk_bf16_f32 v209, v238, v239
	v_cvt_pk_bf16_f32 v210, v230, v231
	v_cvt_pk_bf16_f32 v211, v2, v3
	global_store_dwordx4 v240, v[208:211], s[4:5]
	global_load_dwordx4 v[156:159], v228, s[0:1] nt
	s_add_u32 s0, s0, 0x2000
	s_addc_u32 s1, s1, 0
	v_lshlrev_b32_e32 v208, 16, v160
	v_and_b32_e32 v209, 0xffff0000, v160
	v_lshlrev_b32_e32 v210, 16, v161
	v_and_b32_e32 v211, 0xffff0000, v161
	v_lshlrev_b32_e32 v212, 16, v162
	v_and_b32_e32 v213, 0xffff0000, v162
	v_lshlrev_b32_e32 v214, 16, v163
	v_and_b32_e32 v215, 0xffff0000, v163
	v_pk_mul_f32 v[236:237], v[72:73], v[208:209]
	v_pk_mul_f32 v[238:239], v[74:75], v[210:211]
	v_pk_mul_f32 v[230:231], v[68:69], v[212:213]
	v_pk_mul_f32 v[2:3], v[70:71], v[214:215]
	v_cvt_pk_bf16_f32 v208, v236, v237
	v_cvt_pk_bf16_f32 v209, v238, v239
	v_cvt_pk_bf16_f32 v210, v230, v231
	v_cvt_pk_bf16_f32 v211, v2, v3
	global_store_dwordx4 v240, v[208:211], s[4:5] offset:256
	s_add_u32 s4, s4, 0x28000
	s_addc_u32 s5, s5, 0
	global_load_dwordx4 v[160:163], v228, s[0:1] nt
	s_add_u32 s0, s0, 0x2000
	s_addc_u32 s1, s1, 0
	s_waitcnt vmcnt(14)
	v_lshlrev_b32_e32 v208, 16, v132
	v_and_b32_e32 v209, 0xffff0000, v132
	v_lshlrev_b32_e32 v210, 16, v133
	v_and_b32_e32 v211, 0xffff0000, v133
	v_lshlrev_b32_e32 v212, 16, v134
	v_and_b32_e32 v213, 0xffff0000, v134
	v_lshlrev_b32_e32 v214, 16, v135
	v_and_b32_e32 v215, 0xffff0000, v135
	v_pk_mul_f32 v[236:237], v[64:65], v[208:209]
	v_pk_mul_f32 v[238:239], v[66:67], v[210:211]
	v_pk_mul_f32 v[230:231], v[60:61], v[212:213]
	v_pk_mul_f32 v[2:3], v[62:63], v[214:215]
	v_cvt_pk_bf16_f32 v208, v236, v237
	v_cvt_pk_bf16_f32 v209, v238, v239
	v_cvt_pk_bf16_f32 v210, v230, v231
	v_cvt_pk_bf16_f32 v211, v2, v3
	global_store_dwordx4 v240, v[208:211], s[4:5]
	s_waitcnt vmcnt(13)
	v_lshlrev_b32_e32 v208, 16, v136
	v_and_b32_e32 v209, 0xffff0000, v136
	v_lshlrev_b32_e32 v210, 16, v137
	v_and_b32_e32 v211, 0xffff0000, v137
	v_lshlrev_b32_e32 v212, 16, v138
	v_and_b32_e32 v213, 0xffff0000, v138
	v_lshlrev_b32_e32 v214, 16, v139
	v_and_b32_e32 v215, 0xffff0000, v139
	v_pk_mul_f32 v[236:237], v[32:33], v[208:209]
	v_pk_mul_f32 v[238:239], v[34:35], v[210:211]
	v_pk_mul_f32 v[230:231], v[28:29], v[212:213]
	v_pk_mul_f32 v[2:3], v[30:31], v[214:215]
	v_cvt_pk_bf16_f32 v208, v236, v237
	v_cvt_pk_bf16_f32 v209, v238, v239
	v_cvt_pk_bf16_f32 v210, v230, v231
	v_cvt_pk_bf16_f32 v211, v2, v3
	global_store_dwordx4 v240, v[208:211], s[4:5] offset:256
	s_add_u32 s4, s4, 0x8000
	s_addc_u32 s5, s5, 0
	s_waitcnt vmcnt(12)
	v_lshlrev_b32_e32 v208, 16, v140
	v_and_b32_e32 v209, 0xffff0000, v140
	v_lshlrev_b32_e32 v210, 16, v141
	v_and_b32_e32 v211, 0xffff0000, v141
	v_lshlrev_b32_e32 v212, 16, v142
	v_and_b32_e32 v213, 0xffff0000, v142
	v_lshlrev_b32_e32 v214, 16, v143
	v_and_b32_e32 v215, 0xffff0000, v143
	v_pk_mul_f32 v[236:237], v[56:57], v[208:209]
	v_pk_mul_f32 v[238:239], v[58:59], v[210:211]
	v_pk_mul_f32 v[230:231], v[52:53], v[212:213]
	v_pk_mul_f32 v[2:3], v[54:55], v[214:215]
	v_cvt_pk_bf16_f32 v208, v236, v237
	v_cvt_pk_bf16_f32 v209, v238, v239
	v_cvt_pk_bf16_f32 v210, v230, v231
	v_cvt_pk_bf16_f32 v211, v2, v3
	global_store_dwordx4 v240, v[208:211], s[4:5]
	s_waitcnt vmcnt(11)
	v_lshlrev_b32_e32 v208, 16, v144
	v_and_b32_e32 v209, 0xffff0000, v144
	v_lshlrev_b32_e32 v210, 16, v145
	v_and_b32_e32 v211, 0xffff0000, v145
	v_lshlrev_b32_e32 v212, 16, v146
	v_and_b32_e32 v213, 0xffff0000, v146
	v_lshlrev_b32_e32 v214, 16, v147
	v_and_b32_e32 v215, 0xffff0000, v147
	v_pk_mul_f32 v[236:237], v[24:25], v[208:209]
	v_pk_mul_f32 v[238:239], v[26:27], v[210:211]
	v_pk_mul_f32 v[230:231], v[20:21], v[212:213]
	v_pk_mul_f32 v[2:3], v[22:23], v[214:215]
	v_cvt_pk_bf16_f32 v208, v236, v237
	v_cvt_pk_bf16_f32 v209, v238, v239
	v_cvt_pk_bf16_f32 v210, v230, v231
	v_cvt_pk_bf16_f32 v211, v2, v3
	global_store_dwordx4 v240, v[208:211], s[4:5] offset:256
	s_add_u32 s4, s4, 0x8000
	s_addc_u32 s5, s5, 0
	s_waitcnt vmcnt(10)
	v_lshlrev_b32_e32 v208, 16, v148
	v_and_b32_e32 v209, 0xffff0000, v148
	v_lshlrev_b32_e32 v210, 16, v149
	v_and_b32_e32 v211, 0xffff0000, v149
	v_lshlrev_b32_e32 v212, 16, v150
	v_and_b32_e32 v213, 0xffff0000, v150
	v_lshlrev_b32_e32 v214, 16, v151
	v_and_b32_e32 v215, 0xffff0000, v151
	v_pk_mul_f32 v[236:237], v[48:49], v[208:209]
	v_pk_mul_f32 v[238:239], v[50:51], v[210:211]
	v_pk_mul_f32 v[230:231], v[44:45], v[212:213]
	v_pk_mul_f32 v[2:3], v[46:47], v[214:215]
	v_cvt_pk_bf16_f32 v208, v236, v237
	v_cvt_pk_bf16_f32 v209, v238, v239
	v_cvt_pk_bf16_f32 v210, v230, v231
	v_cvt_pk_bf16_f32 v211, v2, v3
	global_store_dwordx4 v240, v[208:211], s[4:5]
	s_waitcnt vmcnt(9)
	v_lshlrev_b32_e32 v208, 16, v152
	v_and_b32_e32 v209, 0xffff0000, v152
	v_lshlrev_b32_e32 v210, 16, v153
	v_and_b32_e32 v211, 0xffff0000, v153
	v_lshlrev_b32_e32 v212, 16, v154
	v_and_b32_e32 v213, 0xffff0000, v154
	v_lshlrev_b32_e32 v214, 16, v155
	v_and_b32_e32 v215, 0xffff0000, v155
	v_pk_mul_f32 v[236:237], v[16:17], v[208:209]
	v_pk_mul_f32 v[238:239], v[18:19], v[210:211]
	v_pk_mul_f32 v[230:231], v[12:13], v[212:213]
	v_pk_mul_f32 v[2:3], v[14:15], v[214:215]
	v_cvt_pk_bf16_f32 v208, v236, v237
	v_cvt_pk_bf16_f32 v209, v238, v239
	v_cvt_pk_bf16_f32 v210, v230, v231
	v_cvt_pk_bf16_f32 v211, v2, v3
	global_store_dwordx4 v240, v[208:211], s[4:5] offset:256
	s_add_u32 s4, s4, 0x8000
	s_addc_u32 s5, s5, 0
	s_waitcnt vmcnt(8)
	v_lshlrev_b32_e32 v208, 16, v156
	v_and_b32_e32 v209, 0xffff0000, v156
	v_lshlrev_b32_e32 v210, 16, v157
	v_and_b32_e32 v211, 0xffff0000, v157
	v_lshlrev_b32_e32 v212, 16, v158
	v_and_b32_e32 v213, 0xffff0000, v158
	v_lshlrev_b32_e32 v214, 16, v159
	v_and_b32_e32 v215, 0xffff0000, v159
	v_pk_mul_f32 v[236:237], v[40:41], v[208:209]
	v_pk_mul_f32 v[238:239], v[42:43], v[210:211]
	v_pk_mul_f32 v[230:231], v[36:37], v[212:213]
	v_pk_mul_f32 v[2:3], v[38:39], v[214:215]
	v_cvt_pk_bf16_f32 v208, v236, v237
	v_cvt_pk_bf16_f32 v209, v238, v239
	v_cvt_pk_bf16_f32 v210, v230, v231
	v_cvt_pk_bf16_f32 v211, v2, v3
	global_store_dwordx4 v240, v[208:211], s[4:5]
	s_waitcnt vmcnt(7)
	v_lshlrev_b32_e32 v208, 16, v160
	v_and_b32_e32 v209, 0xffff0000, v160
	v_lshlrev_b32_e32 v210, 16, v161
	v_and_b32_e32 v211, 0xffff0000, v161
	v_lshlrev_b32_e32 v212, 16, v162
	v_and_b32_e32 v213, 0xffff0000, v162
	v_lshlrev_b32_e32 v214, 16, v163
	v_and_b32_e32 v215, 0xffff0000, v163
	v_pk_mul_f32 v[236:237], v[8:9], v[208:209]
	v_pk_mul_f32 v[238:239], v[10:11], v[210:211]
	v_pk_mul_f32 v[230:231], v[4:5], v[212:213]
	v_pk_mul_f32 v[2:3], v[6:7], v[214:215]
	v_cvt_pk_bf16_f32 v208, v236, v237
	v_cvt_pk_bf16_f32 v209, v238, v239
	v_cvt_pk_bf16_f32 v210, v230, v231
	v_cvt_pk_bf16_f32 v211, v2, v3
	global_store_dwordx4 v240, v[208:211], s[4:5] offset:256
